# as previous + same change in A and B loops: waves 0-3 take the tile barrier before their last 4 P.V MFMAs
# baseline (speedup 1.0000x reference)
; #define SBAR() __builtin_amdgcn_sched_barrier(0)
; template <int D0> __device__ __forceinline__ void pv_one(f32x16& od, int vb, bf16x8 pa0, bf16x8 pa1, bf16x8 pa2, bf16x8 pa3) {
;     const s16x4 l0 = tr_read<v_rd_off(D0, 0, 0)>(vb), h0 = tr_read<v_rd_off(D0, 0, 1)>(vb), l1 = tr_read<v_rd_off(D0, 1, 0)>(vb), h1 = tr_read<v_rd_off(D0, 1, 1)>(vb);
;     const s16x4 l2 = tr_read<v_rd_off(D0, 2, 0)>(vb), h2 = tr_read<v_rd_off(D0, 2, 1)>(vb), l3 = tr_read<v_rd_off(D0, 3, 0)>(vb), h3 = tr_read<v_rd_off(D0, 3, 1)>(vb);
;     asm volatile("s_waitcnt lgkmcnt(0)" ::: "memory"); SBAR();
;     ...
;     od = __builtin_amdgcn_mfma_f32_32x32x16_bf16(pa0, PK(l0, h0), od, 0, 0, 0);
;     od = __builtin_amdgcn_mfma_f32_32x32x16_bf16(pa1, PK(l1, h1), od, 0, 0, 0);
;     od = __builtin_amdgcn_mfma_f32_32x32x16_bf16(pa2, PK(l2, h2), od, 0, 0, 0);
;     od = __builtin_amdgcn_mfma_f32_32x32x16_bf16(pa3, PK(l3, h3), od, 0, 0, 0);
;     ...
; }
; template <bool RSM> __device__ __forceinline__ void pv_d0(f32x16* o, f32x16& lacc, int vb, bf16x8 pa0, bf16x8 pa1, bf16x8 pa2, bf16x8 pa3) {
;     if (RSM) {
;         const bf16x8 ones = {0x3F80, 0x3F80, 0x3F80, 0x3F80, 0x3F80, 0x3F80, 0x3F80, 0x3F80};
;         lacc = __builtin_amdgcn_mfma_f32_32x32x16_bf16(pa0, ones, lacc, 0, 0, 0);
;         lacc = __builtin_amdgcn_mfma_f32_32x32x16_bf16(pa1, ones, lacc, 0, 0, 0);
;         lacc = __builtin_amdgcn_mfma_f32_32x32x16_bf16(pa2, ones, lacc, 0, 0, 0);
;         lacc = __builtin_amdgcn_mfma_f32_32x32x16_bf16(pa3, ones, lacc, 0, 0, 0); }
;     pv_one<0>(o[0], vb, pa0, pa1, pa2, pa3); pv_one<1>(o[1], vb, pa0, pa1, pa2, pa3); pv_one<2>(o[2], vb, pa0, pa1, pa2, pa3); pv_one<3>(o[3], vb, pa0, pa1, pa2, pa3);
.LBB0_390:
	s_lshl_b32 s19, s16, 14
	v_add_u32_e32 v14, s19, v196
	ds_read_b64_tr_b16 v[100:101], v14 offset:0
	ds_read_b64_tr_b16 v[102:103], v14 offset:0x800
	ds_read_b64_tr_b16 v[104:105], v14 offset:0x1000
	ds_read_b64_tr_b16 v[106:107], v14 offset:0x1800
	ds_read_b64_tr_b16 v[108:109], v14 offset:0x2000
	ds_read_b64_tr_b16 v[110:111], v14 offset:0x2800
	ds_read_b64_tr_b16 v[176:177], v14 offset:0x3000
	ds_read_b64_tr_b16 v[178:179], v14 offset:0x3800
	s_waitcnt lgkmcnt(0)
	s_nop 0
	v_mfma_f32_32x32x16_bf16 v[64:79], v[2:5], v[100:103], v[64:79]
	ds_read_b64_tr_b16 v[100:101], v14 offset:0x200
	ds_read_b64_tr_b16 v[102:103], v14 offset:0xa00
	v_mfma_f32_32x32x16_bf16 v[64:79], v[6:9], v[104:107], v[64:79]
	ds_read_b64_tr_b16 v[104:105], v14 offset:0x1200
	ds_read_b64_tr_b16 v[106:107], v14 offset:0x1a00
	v_mfma_f32_32x32x16_bf16 v[64:79], v[10:13], v[108:111], v[64:79]
	ds_read_b64_tr_b16 v[108:109], v14 offset:0x2200
	ds_read_b64_tr_b16 v[110:111], v14 offset:0x2a00
	v_mfma_f32_32x32x16_bf16 v[64:79], v[96:99], v[176:179], v[64:79]
	ds_read_b64_tr_b16 v[176:177], v14 offset:0x3200
	ds_read_b64_tr_b16 v[178:179], v14 offset:0x3a00
	s_waitcnt lgkmcnt(0)
	v_mfma_f32_32x32x16_bf16 v[48:63], v[2:5], v[100:103], v[48:63]
	ds_read_b64_tr_b16 v[100:101], v14 offset:0x400
	ds_read_b64_tr_b16 v[102:103], v14 offset:0xc00
	v_mfma_f32_32x32x16_bf16 v[48:63], v[6:9], v[104:107], v[48:63]
	ds_read_b64_tr_b16 v[104:105], v14 offset:0x1400
	ds_read_b64_tr_b16 v[106:107], v14 offset:0x1c00
	v_mfma_f32_32x32x16_bf16 v[48:63], v[10:13], v[108:111], v[48:63]
	ds_read_b64_tr_b16 v[108:109], v14 offset:0x2400
	ds_read_b64_tr_b16 v[110:111], v14 offset:0x2c00
	v_mfma_f32_32x32x16_bf16 v[48:63], v[96:99], v[176:179], v[48:63]
	ds_read_b64_tr_b16 v[176:177], v14 offset:0x3400
	ds_read_b64_tr_b16 v[178:179], v14 offset:0x3c00
	s_waitcnt lgkmcnt(0)
	v_mfma_f32_32x32x16_bf16 v[32:47], v[2:5], v[100:103], v[32:47]
	ds_read_b64_tr_b16 v[100:101], v14 offset:0x600
	ds_read_b64_tr_b16 v[102:103], v14 offset:0xe00
	v_mfma_f32_32x32x16_bf16 v[32:47], v[6:9], v[104:107], v[32:47]
	ds_read_b64_tr_b16 v[104:105], v14 offset:0x1600
	ds_read_b64_tr_b16 v[106:107], v14 offset:0x1e00
	v_mfma_f32_32x32x16_bf16 v[32:47], v[10:13], v[108:111], v[32:47]
	ds_read_b64_tr_b16 v[108:109], v14 offset:0x2600
	ds_read_b64_tr_b16 v[110:111], v14 offset:0x2e00
	v_mfma_f32_32x32x16_bf16 v[32:47], v[96:99], v[176:179], v[32:47]
	ds_read_b64_tr_b16 v[176:177], v14 offset:0x3600
	ds_read_b64_tr_b16 v[178:179], v14 offset:0x3e00
	s_waitcnt lgkmcnt(0)
	s_andn2_b64 vcc, exec, s[54:55]
	s_cbranch_vccnz .Lmy_slowab_0
	s_cmpk_gt_u32 s18, 0xfc
	s_cbranch_scc1 .Lmy_slowab_0
	s_mov_b64 s[6:7], -1
	s_add_i32 s6, s81, s13
	s_waitcnt vmcnt(4) lgkmcnt(0)
	s_barrier
	v_mfma_f32_32x32x16_bf16 v[16:31], v[2:5], v[100:103], v[16:31]
	v_cndmask_b32_e64 v2, 0, 1, s[54:55]
	v_cmp_ne_u32_e64 s[0:1], 1, v2
	s_andn2_b64 vcc, exec, s[54:55]
	v_mfma_f32_32x32x16_bf16 v[16:31], v[6:9], v[104:107], v[16:31]
	v_mfma_f32_32x32x16_bf16 v[16:31], v[10:13], v[108:111], v[16:31]
	v_mfma_f32_32x32x16_bf16 v[16:31], v[96:99], v[176:179], v[16:31]
	s_mov_b32 m0, s6
	s_addk_i32 s19, 0xc000
	global_load_lds_dwordx4 v[184:185], off
	s_add_i32 m0, s6, 0x2000
	s_cmp_gt_i32 s16, 0
	s_cselect_b32 s6, s19, 0xc000
	s_add_i32 s6, s63, s6
	global_load_lds_dwordx4 v[188:189], off
	s_mov_b32 m0, s6
	v_lshl_add_u64 v[184:185], v[184:185], 0, s[74:75]
	global_load_lds_dwordx4 v[186:187], off
	s_add_i32 m0, s6, 0x2000
	v_lshl_add_u64 v[188:189], v[188:189], 0, s[74:75]
	global_load_lds_dwordx4 v[190:191], off
	v_lshl_add_u64 v[2:3], v[186:187], 0, s[74:75]
	v_lshl_add_u64 v[4:5], v[190:191], 0, s[74:75]
	v_mov_b64_e32 v[190:191], v[4:5]
	v_mov_b64_e32 v[186:187], v[2:3]
	s_branch .LBB0_395
.Lmy_slowab_0:
	v_mfma_f32_32x32x16_bf16 v[16:31], v[2:5], v[100:103], v[16:31]
	v_cndmask_b32_e64 v2, 0, 1, s[54:55]
	v_cmp_ne_u32_e64 s[0:1], 1, v2
	s_andn2_b64 vcc, exec, s[54:55]
	v_mfma_f32_32x32x16_bf16 v[16:31], v[6:9], v[104:107], v[16:31]
	v_mfma_f32_32x32x16_bf16 v[16:31], v[10:13], v[108:111], v[16:31]
	v_mfma_f32_32x32x16_bf16 v[16:31], v[96:99], v[176:179], v[16:31]
	s_cbranch_vccnz .LBB0_395

; #define SBAR() __builtin_amdgcn_sched_barrier(0)
; template <int D0> __device__ __forceinline__ void pv_one(f32x16& od, int vb, bf16x8 pa0, bf16x8 pa1, bf16x8 pa2, bf16x8 pa3) {
;     const s16x4 l0 = tr_read<v_rd_off(D0, 0, 0)>(vb), h0 = tr_read<v_rd_off(D0, 0, 1)>(vb), l1 = tr_read<v_rd_off(D0, 1, 0)>(vb), h1 = tr_read<v_rd_off(D0, 1, 1)>(vb);
;     const s16x4 l2 = tr_read<v_rd_off(D0, 2, 0)>(vb), h2 = tr_read<v_rd_off(D0, 2, 1)>(vb), l3 = tr_read<v_rd_off(D0, 3, 0)>(vb), h3 = tr_read<v_rd_off(D0, 3, 1)>(vb);
;     asm volatile("s_waitcnt lgkmcnt(0)" ::: "memory"); SBAR();
;     ...
;     od = __builtin_amdgcn_mfma_f32_32x32x16_bf16(pa0, PK(l0, h0), od, 0, 0, 0);
;     od = __builtin_amdgcn_mfma_f32_32x32x16_bf16(pa1, PK(l1, h1), od, 0, 0, 0);
;     od = __builtin_amdgcn_mfma_f32_32x32x16_bf16(pa2, PK(l2, h2), od, 0, 0, 0);
;     od = __builtin_amdgcn_mfma_f32_32x32x16_bf16(pa3, PK(l3, h3), od, 0, 0, 0);
;     ...
; }
; template <bool RSM> __device__ __forceinline__ void pv_d0(f32x16* o, f32x16& lacc, int vb, bf16x8 pa0, bf16x8 pa1, bf16x8 pa2, bf16x8 pa3) {
;     if (RSM) {
;         const bf16x8 ones = {0x3F80, 0x3F80, 0x3F80, 0x3F80, 0x3F80, 0x3F80, 0x3F80, 0x3F80};
;         lacc = __builtin_amdgcn_mfma_f32_32x32x16_bf16(pa0, ones, lacc, 0, 0, 0);
;         lacc = __builtin_amdgcn_mfma_f32_32x32x16_bf16(pa1, ones, lacc, 0, 0, 0);
;         lacc = __builtin_amdgcn_mfma_f32_32x32x16_bf16(pa2, ones, lacc, 0, 0, 0);
;         lacc = __builtin_amdgcn_mfma_f32_32x32x16_bf16(pa3, ones, lacc, 0, 0, 0); }
;     pv_one<0>(o[0], vb, pa0, pa1, pa2, pa3); pv_one<1>(o[1], vb, pa0, pa1, pa2, pa3); pv_one<2>(o[2], vb, pa0, pa1, pa2, pa3); pv_one<3>(o[3], vb, pa0, pa1, pa2, pa3);
.LBB0_402:
	s_lshl_b32 s12, s13, 14
	v_add_u32_e32 v117, s12, v196
	ds_read_b64_tr_b16 v[118:119], v117 offset:0
	ds_read_b64_tr_b16 v[120:121], v117 offset:0x800
	ds_read_b64_tr_b16 v[122:123], v117 offset:0x1000
	ds_read_b64_tr_b16 v[124:125], v117 offset:0x1800
	ds_read_b64_tr_b16 v[176:177], v117 offset:0x2000
	ds_read_b64_tr_b16 v[178:179], v117 offset:0x2800
	ds_read_b64_tr_b16 v[180:181], v117 offset:0x3000
	ds_read_b64_tr_b16 v[182:183], v117 offset:0x3800
	s_waitcnt lgkmcnt(0)
	s_nop 0
	v_mfma_f32_32x32x16_bf16 v[64:79], v[2:5], v[118:121], v[64:79]
	ds_read_b64_tr_b16 v[118:119], v117 offset:0x200
	ds_read_b64_tr_b16 v[120:121], v117 offset:0xa00
	v_mfma_f32_32x32x16_bf16 v[64:79], v[6:9], v[122:125], v[64:79]
	ds_read_b64_tr_b16 v[122:123], v117 offset:0x1200
	ds_read_b64_tr_b16 v[124:125], v117 offset:0x1a00
	v_mfma_f32_32x32x16_bf16 v[64:79], v[10:13], v[176:179], v[64:79]
	ds_read_b64_tr_b16 v[176:177], v117 offset:0x2200
	ds_read_b64_tr_b16 v[178:179], v117 offset:0x2a00
	v_mfma_f32_32x32x16_bf16 v[64:79], v[112:115], v[180:183], v[64:79]
	ds_read_b64_tr_b16 v[180:181], v117 offset:0x3200
	ds_read_b64_tr_b16 v[182:183], v117 offset:0x3a00
	s_waitcnt lgkmcnt(0)
	v_mfma_f32_32x32x16_bf16 v[48:63], v[2:5], v[118:121], v[48:63]
	ds_read_b64_tr_b16 v[118:119], v117 offset:0x400
	ds_read_b64_tr_b16 v[120:121], v117 offset:0xc00
	v_mfma_f32_32x32x16_bf16 v[48:63], v[6:9], v[122:125], v[48:63]
	ds_read_b64_tr_b16 v[122:123], v117 offset:0x1400
	ds_read_b64_tr_b16 v[124:125], v117 offset:0x1c00
	v_mfma_f32_32x32x16_bf16 v[48:63], v[10:13], v[176:179], v[48:63]
	ds_read_b64_tr_b16 v[176:177], v117 offset:0x2400
	ds_read_b64_tr_b16 v[178:179], v117 offset:0x2c00
	v_mfma_f32_32x32x16_bf16 v[48:63], v[112:115], v[180:183], v[48:63]
	ds_read_b64_tr_b16 v[180:181], v117 offset:0x3400
	ds_read_b64_tr_b16 v[182:183], v117 offset:0x3c00
	s_waitcnt lgkmcnt(0)
	v_mfma_f32_32x32x16_bf16 v[32:47], v[2:5], v[118:121], v[32:47]
	ds_read_b64_tr_b16 v[118:119], v117 offset:0x600
	ds_read_b64_tr_b16 v[120:121], v117 offset:0xe00
	v_mfma_f32_32x32x16_bf16 v[32:47], v[6:9], v[122:125], v[32:47]
	ds_read_b64_tr_b16 v[122:123], v117 offset:0x1600
	ds_read_b64_tr_b16 v[124:125], v117 offset:0x1e00
	v_mfma_f32_32x32x16_bf16 v[32:47], v[10:13], v[176:179], v[32:47]
	ds_read_b64_tr_b16 v[176:177], v117 offset:0x2600
	ds_read_b64_tr_b16 v[178:179], v117 offset:0x2e00
	v_mfma_f32_32x32x16_bf16 v[32:47], v[112:115], v[180:183], v[32:47]
	ds_read_b64_tr_b16 v[180:181], v117 offset:0x3600
	ds_read_b64_tr_b16 v[182:183], v117 offset:0x3e00
	s_waitcnt lgkmcnt(0)
	s_and_b64 vcc, exec, s[0:1]
	s_cbranch_vccnz .Lmy_slowab_1
	s_cmpk_gt_u32 s18, 0xfb
	s_cbranch_scc1 .Lmy_slowab_1
	s_mov_b64 s[6:7], -1
	s_add_i32 s6, s81, s20
	s_waitcnt vmcnt(4) lgkmcnt(0)
	s_barrier
	v_mfma_f32_32x32x16_bf16 v[16:31], v[2:5], v[118:121], v[16:31]
	s_and_b64 vcc, exec, s[0:1]
	v_mfma_f32_32x32x16_bf16 v[16:31], v[6:9], v[122:125], v[16:31]
	v_mfma_f32_32x32x16_bf16 v[16:31], v[10:13], v[176:179], v[16:31]
	v_mfma_f32_32x32x16_bf16 v[16:31], v[112:115], v[180:183], v[16:31]
	s_mov_b32 m0, s6
	s_addk_i32 s12, 0xc000
	global_load_lds_dwordx4 v[184:185], off
	s_add_i32 m0, s6, 0x2000
	s_cmp_gt_i32 s13, 0
	s_cselect_b32 s6, s12, 0xc000
	s_add_i32 s6, s63, s6
	global_load_lds_dwordx4 v[188:189], off
	s_mov_b32 m0, s6
	v_lshl_add_u64 v[184:185], v[184:185], 0, s[74:75]
	global_load_lds_dwordx4 v[186:187], off
	s_add_i32 m0, s6, 0x2000
	v_lshl_add_u64 v[188:189], v[188:189], 0, s[74:75]
	global_load_lds_dwordx4 v[190:191], off
	v_lshl_add_u64 v[186:187], v[186:187], 0, s[74:75]
	v_lshl_add_u64 v[190:191], v[190:191], 0, s[74:75]
	s_branch .LBB0_406
.Lmy_slowab_1:
	v_mfma_f32_32x32x16_bf16 v[16:31], v[2:5], v[118:121], v[16:31]
	s_and_b64 vcc, exec, s[0:1]
	v_mfma_f32_32x32x16_bf16 v[16:31], v[6:9], v[122:125], v[16:31]
	v_mfma_f32_32x32x16_bf16 v[16:31], v[10:13], v[176:179], v[16:31]
	v_mfma_f32_32x32x16_bf16 v[16:31], v[112:115], v[180:183], v[16:31]
	s_cbranch_vccnz .LBB0_406

; #define SBAR() __builtin_amdgcn_sched_barrier(0)
; template <int D0> __device__ __forceinline__ void pv_one(f32x16& od, int vb, bf16x8 pa0, bf16x8 pa1, bf16x8 pa2, bf16x8 pa3) {
;     const s16x4 l0 = tr_read<v_rd_off(D0, 0, 0)>(vb), h0 = tr_read<v_rd_off(D0, 0, 1)>(vb), l1 = tr_read<v_rd_off(D0, 1, 0)>(vb), h1 = tr_read<v_rd_off(D0, 1, 1)>(vb);
;     const s16x4 l2 = tr_read<v_rd_off(D0, 2, 0)>(vb), h2 = tr_read<v_rd_off(D0, 2, 1)>(vb), l3 = tr_read<v_rd_off(D0, 3, 0)>(vb), h3 = tr_read<v_rd_off(D0, 3, 1)>(vb);
;     asm volatile("s_waitcnt lgkmcnt(0)" ::: "memory"); SBAR();
;     ...
;     od = __builtin_amdgcn_mfma_f32_32x32x16_bf16(pa0, PK(l0, h0), od, 0, 0, 0);
;     od = __builtin_amdgcn_mfma_f32_32x32x16_bf16(pa1, PK(l1, h1), od, 0, 0, 0);
;     od = __builtin_amdgcn_mfma_f32_32x32x16_bf16(pa2, PK(l2, h2), od, 0, 0, 0);
;     od = __builtin_amdgcn_mfma_f32_32x32x16_bf16(pa3, PK(l3, h3), od, 0, 0, 0);
;     ...
; }
; template <bool RSM> __device__ __forceinline__ void pv_d0(f32x16* o, f32x16& lacc, int vb, bf16x8 pa0, bf16x8 pa1, bf16x8 pa2, bf16x8 pa3) {
;     if (RSM) {
;         const bf16x8 ones = {0x3F80, 0x3F80, 0x3F80, 0x3F80, 0x3F80, 0x3F80, 0x3F80, 0x3F80};
;         lacc = __builtin_amdgcn_mfma_f32_32x32x16_bf16(pa0, ones, lacc, 0, 0, 0);
;         lacc = __builtin_amdgcn_mfma_f32_32x32x16_bf16(pa1, ones, lacc, 0, 0, 0);
;         lacc = __builtin_amdgcn_mfma_f32_32x32x16_bf16(pa2, ones, lacc, 0, 0, 0);
;         lacc = __builtin_amdgcn_mfma_f32_32x32x16_bf16(pa3, ones, lacc, 0, 0, 0); }
;     pv_one<0>(o[0], vb, pa0, pa1, pa2, pa3); pv_one<1>(o[1], vb, pa0, pa1, pa2, pa3); pv_one<2>(o[2], vb, pa0, pa1, pa2, pa3); pv_one<3>(o[3], vb, pa0, pa1, pa2, pa3);
.LBB0_444:
	s_lshl_b32 s18, s12, 14
	v_add_u32_e32 v197, s18, v177
	ds_read_b64_tr_b16 v[172:173], v197 offset:0
	ds_read_b64_tr_b16 v[174:175], v197 offset:0x800
	ds_read_b64_tr_b16 v[198:199], v197 offset:0x1000
	ds_read_b64_tr_b16 v[200:201], v197 offset:0x1800
	ds_read_b64_tr_b16 v[208:209], v197 offset:0x2000
	ds_read_b64_tr_b16 v[210:211], v197 offset:0x2800
	ds_read_b64_tr_b16 v[212:213], v197 offset:0x3000
	ds_read_b64_tr_b16 v[214:215], v197 offset:0x3800
	s_waitcnt lgkmcnt(0)
	s_nop 0
	v_mfma_f32_32x32x16_bf16 v[50:65], v[146:149], v[172:175], v[50:65]
	ds_read_b64_tr_b16 v[172:173], v197 offset:0x200
	ds_read_b64_tr_b16 v[174:175], v197 offset:0xa00
	v_mfma_f32_32x32x16_bf16 v[50:65], v[150:153], v[198:201], v[50:65]
	ds_read_b64_tr_b16 v[198:199], v197 offset:0x1200
	ds_read_b64_tr_b16 v[200:201], v197 offset:0x1a00
	v_mfma_f32_32x32x16_bf16 v[50:65], v[154:157], v[208:211], v[50:65]
	ds_read_b64_tr_b16 v[208:209], v197 offset:0x2200
	ds_read_b64_tr_b16 v[210:211], v197 offset:0x2a00
	v_mfma_f32_32x32x16_bf16 v[50:65], v[158:161], v[212:215], v[50:65]
	ds_read_b64_tr_b16 v[212:213], v197 offset:0x3200
	ds_read_b64_tr_b16 v[214:215], v197 offset:0x3a00
	s_waitcnt lgkmcnt(0)
	v_mfma_f32_32x32x16_bf16 v[34:49], v[146:149], v[172:175], v[34:49]
	ds_read_b64_tr_b16 v[172:173], v197 offset:0x400
	ds_read_b64_tr_b16 v[174:175], v197 offset:0xc00
	v_mfma_f32_32x32x16_bf16 v[34:49], v[150:153], v[198:201], v[34:49]
	ds_read_b64_tr_b16 v[198:199], v197 offset:0x1400
	ds_read_b64_tr_b16 v[200:201], v197 offset:0x1c00
	v_mfma_f32_32x32x16_bf16 v[34:49], v[154:157], v[208:211], v[34:49]
	ds_read_b64_tr_b16 v[208:209], v197 offset:0x2400
	ds_read_b64_tr_b16 v[210:211], v197 offset:0x2c00
	v_mfma_f32_32x32x16_bf16 v[34:49], v[158:161], v[212:215], v[34:49]
	ds_read_b64_tr_b16 v[212:213], v197 offset:0x3400
	ds_read_b64_tr_b16 v[214:215], v197 offset:0x3c00
	s_waitcnt lgkmcnt(0)
	v_mfma_f32_32x32x16_bf16 v[18:33], v[146:149], v[172:175], v[18:33]
	ds_read_b64_tr_b16 v[172:173], v197 offset:0x600
	ds_read_b64_tr_b16 v[174:175], v197 offset:0xe00
	v_mfma_f32_32x32x16_bf16 v[18:33], v[150:153], v[198:201], v[18:33]
	ds_read_b64_tr_b16 v[198:199], v197 offset:0x1600
	ds_read_b64_tr_b16 v[200:201], v197 offset:0x1e00
	v_mfma_f32_32x32x16_bf16 v[18:33], v[154:157], v[208:211], v[18:33]
	ds_read_b64_tr_b16 v[208:209], v197 offset:0x2600
	ds_read_b64_tr_b16 v[210:211], v197 offset:0x2e00
	v_mfma_f32_32x32x16_bf16 v[18:33], v[158:161], v[212:215], v[18:33]
	ds_read_b64_tr_b16 v[212:213], v197 offset:0x3600
	ds_read_b64_tr_b16 v[214:215], v197 offset:0x3e00
	s_waitcnt lgkmcnt(0)
	s_and_b64 vcc, exec, s[0:1]
	s_cbranch_vccnz .Lmy_slowab_2
	s_cmpk_gt_u32 s17, 0xfc
	s_cbranch_scc1 .Lmy_slowab_2
	s_mov_b64 s[14:15], -1
	s_add_i32 s13, s81, s13
	s_waitcnt vmcnt(5) lgkmcnt(0)
	s_barrier
	v_mfma_f32_32x32x16_bf16 v[2:17], v[146:149], v[172:175], v[2:17]
	s_and_b64 vcc, exec, s[0:1]
	v_mfma_f32_32x32x16_bf16 v[2:17], v[150:153], v[198:201], v[2:17]
	v_mfma_f32_32x32x16_bf16 v[2:17], v[154:157], v[208:211], v[2:17]
	v_mfma_f32_32x32x16_bf16 v[2:17], v[158:161], v[212:215], v[2:17]
	s_mov_b32 m0, s13
	s_addk_i32 s18, 0xc000
	global_load_lds_dwordx4 v[162:163], off
	s_add_i32 m0, s13, 0x2000
	v_lshl_add_u64 v[162:163], v[162:163], 0, s[94:95]
	global_load_lds_dwordx4 v[164:165], off
	s_add_i32 m0, s13, 0x4000
	s_cmp_gt_i32 s12, 0
	s_cselect_b32 s13, s18, 0xc000
	s_add_i32 s13, s63, s13
	global_load_lds_dwordx4 v[166:167], off
	s_mov_b32 m0, s13
	v_lshl_add_u64 v[164:165], v[164:165], 0, s[94:95]
	global_load_lds_dwordx4 v[170:171], off
	s_add_i32 m0, s13, 0x2000
	v_lshl_add_u64 v[166:167], v[166:167], 0, s[74:75]
	global_load_lds_dwordx4 v[168:169], off
	v_lshl_add_u64 v[146:147], v[170:171], 0, s[94:95]
	v_lshl_add_u64 v[148:149], v[168:169], 0, s[94:95]
	v_mov_b64_e32 v[168:169], v[148:149]
	v_mov_b64_e32 v[170:171], v[146:147]
	s_branch .LBB0_449
.Lmy_slowab_2:
	v_mfma_f32_32x32x16_bf16 v[2:17], v[146:149], v[172:175], v[2:17]
	s_and_b64 vcc, exec, s[0:1]
	v_mfma_f32_32x32x16_bf16 v[2:17], v[150:153], v[198:201], v[2:17]
	v_mfma_f32_32x32x16_bf16 v[2:17], v[154:157], v[208:211], v[2:17]
	v_mfma_f32_32x32x16_bf16 v[2:17], v[158:161], v[212:215], v[2:17]
	s_cbranch_vccnz .LBB0_449

; #define SBAR() __builtin_amdgcn_sched_barrier(0)
; template <int D0> __device__ __forceinline__ void pv_one(f32x16& od, int vb, bf16x8 pa0, bf16x8 pa1, bf16x8 pa2, bf16x8 pa3) {
;     const s16x4 l0 = tr_read<v_rd_off(D0, 0, 0)>(vb), h0 = tr_read<v_rd_off(D0, 0, 1)>(vb), l1 = tr_read<v_rd_off(D0, 1, 0)>(vb), h1 = tr_read<v_rd_off(D0, 1, 1)>(vb);
;     const s16x4 l2 = tr_read<v_rd_off(D0, 2, 0)>(vb), h2 = tr_read<v_rd_off(D0, 2, 1)>(vb), l3 = tr_read<v_rd_off(D0, 3, 0)>(vb), h3 = tr_read<v_rd_off(D0, 3, 1)>(vb);
;     asm volatile("s_waitcnt lgkmcnt(0)" ::: "memory"); SBAR();
;     ...
;     od = __builtin_amdgcn_mfma_f32_32x32x16_bf16(pa0, PK(l0, h0), od, 0, 0, 0);
;     od = __builtin_amdgcn_mfma_f32_32x32x16_bf16(pa1, PK(l1, h1), od, 0, 0, 0);
;     od = __builtin_amdgcn_mfma_f32_32x32x16_bf16(pa2, PK(l2, h2), od, 0, 0, 0);
;     od = __builtin_amdgcn_mfma_f32_32x32x16_bf16(pa3, PK(l3, h3), od, 0, 0, 0);
;     ...
; }
; template <bool RSM> __device__ __forceinline__ void pv_d0(f32x16* o, f32x16& lacc, int vb, bf16x8 pa0, bf16x8 pa1, bf16x8 pa2, bf16x8 pa3) {
;     if (RSM) {
;         const bf16x8 ones = {0x3F80, 0x3F80, 0x3F80, 0x3F80, 0x3F80, 0x3F80, 0x3F80, 0x3F80};
;         lacc = __builtin_amdgcn_mfma_f32_32x32x16_bf16(pa0, ones, lacc, 0, 0, 0);
;         lacc = __builtin_amdgcn_mfma_f32_32x32x16_bf16(pa1, ones, lacc, 0, 0, 0);
;         lacc = __builtin_amdgcn_mfma_f32_32x32x16_bf16(pa2, ones, lacc, 0, 0, 0);
;         lacc = __builtin_amdgcn_mfma_f32_32x32x16_bf16(pa3, ones, lacc, 0, 0, 0); }
;     pv_one<0>(o[0], vb, pa0, pa1, pa2, pa3); pv_one<1>(o[1], vb, pa0, pa1, pa2, pa3); pv_one<2>(o[2], vb, pa0, pa1, pa2, pa3); pv_one<3>(o[3], vb, pa0, pa1, pa2, pa3);
.LBB0_455:
	s_lshl_b32 s19, s15, 14
	v_add_u32_e32 v175, s19, v177
	ds_read_b64_tr_b16 v[198:199], v175 offset:0
	ds_read_b64_tr_b16 v[200:201], v175 offset:0x800
	ds_read_b64_tr_b16 v[208:209], v175 offset:0x1000
	ds_read_b64_tr_b16 v[210:211], v175 offset:0x1800
	ds_read_b64_tr_b16 v[212:213], v175 offset:0x2000
	ds_read_b64_tr_b16 v[214:215], v175 offset:0x2800
	ds_read_b64_tr_b16 v[226:227], v175 offset:0x3000
	ds_read_b64_tr_b16 v[228:229], v175 offset:0x3800
	s_waitcnt lgkmcnt(0)
	s_nop 0
	v_mfma_f32_32x32x16_bf16 v[50:65], v[146:149], v[198:201], v[50:65]
	ds_read_b64_tr_b16 v[198:199], v175 offset:0x200
	ds_read_b64_tr_b16 v[200:201], v175 offset:0xa00
	v_mfma_f32_32x32x16_bf16 v[50:65], v[150:153], v[208:211], v[50:65]
	ds_read_b64_tr_b16 v[208:209], v175 offset:0x1200
	ds_read_b64_tr_b16 v[210:211], v175 offset:0x1a00
	v_mfma_f32_32x32x16_bf16 v[50:65], v[154:157], v[212:215], v[50:65]
	ds_read_b64_tr_b16 v[212:213], v175 offset:0x2200
	ds_read_b64_tr_b16 v[214:215], v175 offset:0x2a00
	v_mfma_f32_32x32x16_bf16 v[50:65], v[158:161], v[226:229], v[50:65]
	ds_read_b64_tr_b16 v[226:227], v175 offset:0x3200
	ds_read_b64_tr_b16 v[228:229], v175 offset:0x3a00
	s_waitcnt lgkmcnt(0)
	v_mfma_f32_32x32x16_bf16 v[34:49], v[146:149], v[198:201], v[34:49]
	ds_read_b64_tr_b16 v[198:199], v175 offset:0x400
	ds_read_b64_tr_b16 v[200:201], v175 offset:0xc00
	v_mfma_f32_32x32x16_bf16 v[34:49], v[150:153], v[208:211], v[34:49]
	ds_read_b64_tr_b16 v[208:209], v175 offset:0x1400
	ds_read_b64_tr_b16 v[210:211], v175 offset:0x1c00
	v_mfma_f32_32x32x16_bf16 v[34:49], v[154:157], v[212:215], v[34:49]
	ds_read_b64_tr_b16 v[212:213], v175 offset:0x2400
	ds_read_b64_tr_b16 v[214:215], v175 offset:0x2c00
	v_mfma_f32_32x32x16_bf16 v[34:49], v[158:161], v[226:229], v[34:49]
	ds_read_b64_tr_b16 v[226:227], v175 offset:0x3400
	ds_read_b64_tr_b16 v[228:229], v175 offset:0x3c00
	s_waitcnt lgkmcnt(0)
	v_mfma_f32_32x32x16_bf16 v[18:33], v[146:149], v[198:201], v[18:33]
	ds_read_b64_tr_b16 v[198:199], v175 offset:0x600
	ds_read_b64_tr_b16 v[200:201], v175 offset:0xe00
	v_mfma_f32_32x32x16_bf16 v[18:33], v[150:153], v[208:211], v[18:33]
	ds_read_b64_tr_b16 v[208:209], v175 offset:0x1600
	ds_read_b64_tr_b16 v[210:211], v175 offset:0x1e00
	v_mfma_f32_32x32x16_bf16 v[18:33], v[154:157], v[212:215], v[18:33]
	ds_read_b64_tr_b16 v[212:213], v175 offset:0x2600
	ds_read_b64_tr_b16 v[214:215], v175 offset:0x2e00
	v_mfma_f32_32x32x16_bf16 v[18:33], v[158:161], v[226:229], v[18:33]
	ds_read_b64_tr_b16 v[226:227], v175 offset:0x3600
	ds_read_b64_tr_b16 v[228:229], v175 offset:0x3e00
	s_waitcnt lgkmcnt(0)
	s_and_b64 vcc, exec, s[0:1]
	s_cbranch_vccnz .Lmy_slowab_3
	s_cmpk_gt_u32 s17, 0xfb
	s_cbranch_scc1 .Lmy_slowab_3
	s_mov_b64 s[12:13], -1
	s_add_i32 s12, s81, s18
	s_waitcnt vmcnt(5) lgkmcnt(0)
	s_barrier
	v_mfma_f32_32x32x16_bf16 v[2:17], v[146:149], v[198:201], v[2:17]
	s_and_b64 vcc, exec, s[0:1]
	v_mfma_f32_32x32x16_bf16 v[2:17], v[150:153], v[208:211], v[2:17]
	v_mfma_f32_32x32x16_bf16 v[2:17], v[154:157], v[212:215], v[2:17]
	v_mfma_f32_32x32x16_bf16 v[2:17], v[158:161], v[226:229], v[2:17]
	s_mov_b32 m0, s12
	s_addk_i32 s19, 0xc000
	global_load_lds_dwordx4 v[162:163], off
	s_add_i32 m0, s12, 0x2000
	v_lshl_add_u64 v[162:163], v[162:163], 0, s[94:95]
	global_load_lds_dwordx4 v[164:165], off
	s_add_i32 m0, s12, 0x4000
	s_cmp_gt_i32 s15, 0
	s_cselect_b32 s12, s19, 0xc000
	s_add_i32 s12, s63, s12
	global_load_lds_dwordx4 v[166:167], off
	s_mov_b32 m0, s12
	v_lshl_add_u64 v[164:165], v[164:165], 0, s[94:95]
	global_load_lds_dwordx4 v[170:171], off
	s_add_i32 m0, s12, 0x2000
	v_lshl_add_u64 v[166:167], v[166:167], 0, s[74:75]
	global_load_lds_dwordx4 v[168:169], off
	v_lshl_add_u64 v[170:171], v[170:171], 0, s[94:95]
	v_lshl_add_u64 v[168:169], v[168:169], 0, s[94:95]
	s_branch .LBB0_459
.Lmy_slowab_3:
	v_mfma_f32_32x32x16_bf16 v[2:17], v[146:149], v[198:201], v[2:17]
	s_and_b64 vcc, exec, s[0:1]
	v_mfma_f32_32x32x16_bf16 v[2:17], v[150:153], v[208:211], v[2:17]
	v_mfma_f32_32x32x16_bf16 v[2:17], v[154:157], v[212:215], v[2:17]
	v_mfma_f32_32x32x16_bf16 v[2:17], v[158:161], v[226:229], v[2:17]
	s_cbranch_vccnz .LBB0_459
